# D4 top-k selection body rewritten lean (batched LDS key loads, quad-granular uniform slot loops, inverted keys + DPP prefix scan + ff1 bin search); same radix-select algorithm
# speedup vs baseline: 1.0274x; 1.0208x over previous
; __device__ __forceinline__ void dsa_index_phase(const Params& p, unsigned char* smem) {
;     ...
;             const int ql = wave * 2 + qq, t = t0 + ql;
;             const float* srow = SC + ql * ROWP;
;             const int ni = (t >> 6) + 1;
;             unsigned u[32];
; #pragma unroll
;             for (int i = 0; i < 32; ++i) {
;                 u[i] = 0u;
;                 if (i < ni) { const int s = i * 64 + lane; if (s <= t) u[i] = fkey(srow[s]); }
;             }
;             unsigned short* selrow = selout + (size_t)(row0 + ql) * 256;
;             if (t < 256) {
; #pragma unroll
;                 for (int i = 0; i < 4; ++i) { const int pp = i * 64 + lane; selrow[pp] = (unsigned short)(pp <= t ? pp : 0xFFFF); }
;             } else {
;                 unsigned* H = (unsigned*)(smem + 16 * ROWP * 4) + wave * 256;
;                 unsigned prefix = 0u; int need = 256;
; #pragma unroll 1
;                 for (int pass = 0; pass < 4; ++pass) {
;                     const int shift = 24 - 8 * pass;
;                     const unsigned hmask = pass == 0 ? 0u : (0xFFFFFFFFu << (shift + 8));
;                     *(u32x4*)(H + lane * 4) = (u32x4){0u, 0u, 0u, 0u};
;                     asm volatile("s_waitcnt lgkmcnt(0)" ::: "memory");
; #pragma unroll
;                     for (int i = 0; i < 32; ++i) if (i < ni) { const unsigned uu = u[i]; if (uu != 0u && (uu & hmask) == prefix) atomicAdd(H + ((uu >> shift) & 255u), 1u); }
.LBB0_126:
	v_or_b32_e32 v121, s0, v154
	v_readlane_b32 s8, v254, 31
	v_readlane_b32 s7, v254, 30
	v_readlane_b32 s12, v250, 21
	v_readlane_b32 s13, v250, 22
	v_readfirstlane_b32 s6, v121
	s_add_i32 s8, s8, s6
	s_add_i32 s7, s7, s6
	s_lshl_b32 s7, s7, 9
	s_add_u32 s12, s12, s7
	s_addc_u32 s13, s13, 0
	s_cmpk_lt_u32 s8, 0x100
	s_cbranch_scc1 .Ltk_small
	s_mul_i32 s6, s6, 0x2010
	s_lshr_b32 s9, s8, 8
	s_lshl_b32 s9, s9, 2
	s_add_i32 s9, s9, 4
	v_lshl_add_u32 v122, v124, 2, s6
	ds_read_b32 v0, v122
	ds_read_b32 v1, v122 offset:256
	ds_read_b32 v2, v122 offset:512
	ds_read_b32 v3, v122 offset:768
	s_cmp_le_u32 s9, 4
	s_cbranch_scc1 .Ltk_ld_end
	ds_read_b32 v4, v122 offset:1024
	ds_read_b32 v5, v122 offset:1280
	ds_read_b32 v6, v122 offset:1536
	ds_read_b32 v7, v122 offset:1792
	s_cmp_le_u32 s9, 8
	s_cbranch_scc1 .Ltk_ld_end
	ds_read_b32 v8, v122 offset:2048
	ds_read_b32 v9, v122 offset:2304
	ds_read_b32 v10, v122 offset:2560
	ds_read_b32 v11, v122 offset:2816
	s_cmp_le_u32 s9, 12
	s_cbranch_scc1 .Ltk_ld_end
	ds_read_b32 v12, v122 offset:3072
	ds_read_b32 v13, v122 offset:3328
	ds_read_b32 v14, v122 offset:3584
	ds_read_b32 v15, v122 offset:3840
	s_cmp_le_u32 s9, 16
	s_cbranch_scc1 .Ltk_ld_end
	ds_read_b32 v16, v122 offset:4096
	ds_read_b32 v17, v122 offset:4352
	ds_read_b32 v18, v122 offset:4608
	ds_read_b32 v19, v122 offset:4864
	s_cmp_le_u32 s9, 20
	s_cbranch_scc1 .Ltk_ld_end
	ds_read_b32 v20, v122 offset:5120
	ds_read_b32 v21, v122 offset:5376
	ds_read_b32 v22, v122 offset:5632
	ds_read_b32 v23, v122 offset:5888
	s_cmp_le_u32 s9, 24
	s_cbranch_scc1 .Ltk_ld_end
	ds_read_b32 v24, v122 offset:6144
	ds_read_b32 v25, v122 offset:6400
	ds_read_b32 v26, v122 offset:6656
	ds_read_b32 v27, v122 offset:6912
	s_cmp_le_u32 s9, 28
	s_cbranch_scc1 .Ltk_ld_end
	ds_read_b32 v28, v122 offset:7168
	ds_read_b32 v29, v122 offset:7424
	ds_read_b32 v30, v122 offset:7680
	ds_read_b32 v31, v122 offset:7936
.Ltk_ld_end:
	s_waitcnt lgkmcnt(0)
	v_add_f32_e32 v0, 0, v0
	v_cmp_ge_u32_e64 s[2:3], s8, v124
	v_ashrrev_i32_e32 v120, 31, v0
	v_or_b32_e32 v120, 0x80000000, v120
	v_xnor_b32_e32 v0, v120, v0
	v_cndmask_b32_e64 v0, -1, v0, s[2:3]
	v_add_f32_e32 v1, 0, v1
	v_cmp_ge_u32_e64 s[4:5], s8, v156
	v_ashrrev_i32_e32 v121, 31, v1
	v_or_b32_e32 v121, 0x80000000, v121
	v_xnor_b32_e32 v1, v121, v1
	v_cndmask_b32_e64 v1, -1, v1, s[4:5]
	v_add_f32_e32 v2, 0, v2
	v_cmp_ge_u32_e64 s[2:3], s8, v157
	v_ashrrev_i32_e32 v120, 31, v2
	v_or_b32_e32 v120, 0x80000000, v120
	v_xnor_b32_e32 v2, v120, v2
	v_cndmask_b32_e64 v2, -1, v2, s[2:3]
	v_add_f32_e32 v3, 0, v3
	v_cmp_ge_u32_e64 s[4:5], s8, v158
	v_ashrrev_i32_e32 v121, 31, v3
	v_or_b32_e32 v121, 0x80000000, v121
	v_xnor_b32_e32 v3, v121, v3
	v_cndmask_b32_e64 v3, -1, v3, s[4:5]
	s_cmp_le_u32 s9, 4
	s_cbranch_scc1 .Ltk_cv_end
	v_add_f32_e32 v4, 0, v4
	v_cmp_ge_u32_e64 s[2:3], s8, v159
	v_ashrrev_i32_e32 v120, 31, v4
	v_or_b32_e32 v120, 0x80000000, v120
	v_xnor_b32_e32 v4, v120, v4
	v_cndmask_b32_e64 v4, -1, v4, s[2:3]
	v_add_f32_e32 v5, 0, v5
	v_cmp_ge_u32_e64 s[4:5], s8, v160
	v_ashrrev_i32_e32 v121, 31, v5
	v_or_b32_e32 v121, 0x80000000, v121
	v_xnor_b32_e32 v5, v121, v5
	v_cndmask_b32_e64 v5, -1, v5, s[4:5]
	v_add_f32_e32 v6, 0, v6
	v_cmp_ge_u32_e64 s[2:3], s8, v161
	v_ashrrev_i32_e32 v120, 31, v6
	v_or_b32_e32 v120, 0x80000000, v120
	v_xnor_b32_e32 v6, v120, v6
	v_cndmask_b32_e64 v6, -1, v6, s[2:3]
	v_add_f32_e32 v7, 0, v7
	v_cmp_ge_u32_e64 s[4:5], s8, v162
	v_ashrrev_i32_e32 v121, 31, v7
	v_or_b32_e32 v121, 0x80000000, v121
	v_xnor_b32_e32 v7, v121, v7
	v_cndmask_b32_e64 v7, -1, v7, s[4:5]
	s_cmp_le_u32 s9, 8
	s_cbranch_scc1 .Ltk_cv_end
	v_add_f32_e32 v8, 0, v8
	v_cmp_ge_u32_e64 s[2:3], s8, v163
	v_ashrrev_i32_e32 v120, 31, v8
	v_or_b32_e32 v120, 0x80000000, v120
	v_xnor_b32_e32 v8, v120, v8
	v_cndmask_b32_e64 v8, -1, v8, s[2:3]
	v_add_f32_e32 v9, 0, v9
	v_cmp_ge_u32_e64 s[4:5], s8, v164
	v_ashrrev_i32_e32 v121, 31, v9
	v_or_b32_e32 v121, 0x80000000, v121
	v_xnor_b32_e32 v9, v121, v9
	v_cndmask_b32_e64 v9, -1, v9, s[4:5]
	v_add_f32_e32 v10, 0, v10
	v_cmp_ge_u32_e64 s[2:3], s8, v165
	v_ashrrev_i32_e32 v120, 31, v10
	v_or_b32_e32 v120, 0x80000000, v120
	v_xnor_b32_e32 v10, v120, v10
	v_cndmask_b32_e64 v10, -1, v10, s[2:3]
	v_add_f32_e32 v11, 0, v11
	v_cmp_ge_u32_e64 s[4:5], s8, v166
	v_ashrrev_i32_e32 v121, 31, v11
	v_or_b32_e32 v121, 0x80000000, v121
	v_xnor_b32_e32 v11, v121, v11
	v_cndmask_b32_e64 v11, -1, v11, s[4:5]
	s_cmp_le_u32 s9, 12
	s_cbranch_scc1 .Ltk_cv_end
	v_add_f32_e32 v12, 0, v12
	v_cmp_ge_u32_e64 s[2:3], s8, v167
	v_ashrrev_i32_e32 v120, 31, v12
	v_or_b32_e32 v120, 0x80000000, v120
	v_xnor_b32_e32 v12, v120, v12
	v_cndmask_b32_e64 v12, -1, v12, s[2:3]
	v_add_f32_e32 v13, 0, v13
	v_cmp_ge_u32_e64 s[4:5], s8, v168
	v_ashrrev_i32_e32 v121, 31, v13
	v_or_b32_e32 v121, 0x80000000, v121
	v_xnor_b32_e32 v13, v121, v13
	v_cndmask_b32_e64 v13, -1, v13, s[4:5]
	v_add_f32_e32 v14, 0, v14
	v_cmp_ge_u32_e64 s[2:3], s8, v169
	v_ashrrev_i32_e32 v120, 31, v14
	v_or_b32_e32 v120, 0x80000000, v120
	v_xnor_b32_e32 v14, v120, v14
	v_cndmask_b32_e64 v14, -1, v14, s[2:3]
	v_add_f32_e32 v15, 0, v15
	v_cmp_ge_u32_e64 s[4:5], s8, v170
	v_ashrrev_i32_e32 v121, 31, v15
	v_or_b32_e32 v121, 0x80000000, v121
	v_xnor_b32_e32 v15, v121, v15
	v_cndmask_b32_e64 v15, -1, v15, s[4:5]
	s_cmp_le_u32 s9, 16
	s_cbranch_scc1 .Ltk_cv_end
; __device__ __forceinline__ void dsa_index_phase(const Params& p, unsigned char* smem) {
;     ...
;             for (int i = 0; i < 32; ++i) {
;                 u[i] = 0u;
;                 if (i < ni) { const int s = i * 64 + lane; if (s <= t) u[i] = fkey(srow[s]); }
;             }
;             unsigned short* selrow = selout + (size_t)(row0 + ql) * 256;
;             if (t < 256) {
; #pragma unroll
;                 for (int i = 0; i < 4; ++i) { const int pp = i * 64 + lane; selrow[pp] = (unsigned short)(pp <= t ? pp : 0xFFFF); }
;             } else {
;                 unsigned* H = (unsigned*)(smem + 16 * ROWP * 4) + wave * 256;
;                 unsigned prefix = 0u; int need = 256;
; #pragma unroll 1
;                 for (int pass = 0; pass < 4; ++pass) {
;                     const int shift = 24 - 8 * pass;
;                     const unsigned hmask = pass == 0 ? 0u : (0xFFFFFFFFu << (shift + 8));
;                     *(u32x4*)(H + lane * 4) = (u32x4){0u, 0u, 0u, 0u};
;                     asm volatile("s_waitcnt lgkmcnt(0)" ::: "memory");
; #pragma unroll
;                     for (int i = 0; i < 32; ++i) if (i < ni) { const unsigned uu = u[i]; if (uu != 0u && (uu & hmask) == prefix) atomicAdd(H + ((uu >> shift) & 255u), 1u); }
	v_add_f32_e32 v16, 0, v16
	v_cmp_ge_u32_e64 s[2:3], s8, v171
	v_ashrrev_i32_e32 v120, 31, v16
	v_or_b32_e32 v120, 0x80000000, v120
	v_xnor_b32_e32 v16, v120, v16
	v_cndmask_b32_e64 v16, -1, v16, s[2:3]
	v_add_f32_e32 v17, 0, v17
	v_cmp_ge_u32_e64 s[4:5], s8, v172
	v_ashrrev_i32_e32 v121, 31, v17
	v_or_b32_e32 v121, 0x80000000, v121
	v_xnor_b32_e32 v17, v121, v17
	v_cndmask_b32_e64 v17, -1, v17, s[4:5]
	v_add_f32_e32 v18, 0, v18
	v_cmp_ge_u32_e64 s[2:3], s8, v173
	v_ashrrev_i32_e32 v120, 31, v18
	v_or_b32_e32 v120, 0x80000000, v120
	v_xnor_b32_e32 v18, v120, v18
	v_cndmask_b32_e64 v18, -1, v18, s[2:3]
	v_add_f32_e32 v19, 0, v19
	v_cmp_ge_u32_e64 s[4:5], s8, v174
	v_ashrrev_i32_e32 v121, 31, v19
	v_or_b32_e32 v121, 0x80000000, v121
	v_xnor_b32_e32 v19, v121, v19
	v_cndmask_b32_e64 v19, -1, v19, s[4:5]
	s_cmp_le_u32 s9, 20
	s_cbranch_scc1 .Ltk_cv_end
	v_add_f32_e32 v20, 0, v20
	v_cmp_ge_u32_e64 s[2:3], s8, v175
	v_ashrrev_i32_e32 v120, 31, v20
	v_or_b32_e32 v120, 0x80000000, v120
	v_xnor_b32_e32 v20, v120, v20
	v_cndmask_b32_e64 v20, -1, v20, s[2:3]
	v_add_f32_e32 v21, 0, v21
	v_cmp_ge_u32_e64 s[4:5], s8, v176
	v_ashrrev_i32_e32 v121, 31, v21
	v_or_b32_e32 v121, 0x80000000, v121
	v_xnor_b32_e32 v21, v121, v21
	v_cndmask_b32_e64 v21, -1, v21, s[4:5]
	v_add_f32_e32 v22, 0, v22
	v_cmp_ge_u32_e64 s[2:3], s8, v177
	v_ashrrev_i32_e32 v120, 31, v22
	v_or_b32_e32 v120, 0x80000000, v120
	v_xnor_b32_e32 v22, v120, v22
	v_cndmask_b32_e64 v22, -1, v22, s[2:3]
	v_add_f32_e32 v23, 0, v23
	v_cmp_ge_u32_e64 s[4:5], s8, v178
	v_ashrrev_i32_e32 v121, 31, v23
	v_or_b32_e32 v121, 0x80000000, v121
	v_xnor_b32_e32 v23, v121, v23
	v_cndmask_b32_e64 v23, -1, v23, s[4:5]
	s_cmp_le_u32 s9, 24
	s_cbranch_scc1 .Ltk_cv_end
	v_add_f32_e32 v24, 0, v24
	v_cmp_ge_u32_e64 s[2:3], s8, v179
	v_ashrrev_i32_e32 v120, 31, v24
	v_or_b32_e32 v120, 0x80000000, v120
	v_xnor_b32_e32 v24, v120, v24
	v_cndmask_b32_e64 v24, -1, v24, s[2:3]
	v_add_f32_e32 v25, 0, v25
	v_cmp_ge_u32_e64 s[4:5], s8, v180
	v_ashrrev_i32_e32 v121, 31, v25
	v_or_b32_e32 v121, 0x80000000, v121
	v_xnor_b32_e32 v25, v121, v25
	v_cndmask_b32_e64 v25, -1, v25, s[4:5]
	v_add_f32_e32 v26, 0, v26
	v_cmp_ge_u32_e64 s[2:3], s8, v181
	v_ashrrev_i32_e32 v120, 31, v26
	v_or_b32_e32 v120, 0x80000000, v120
	v_xnor_b32_e32 v26, v120, v26
	v_cndmask_b32_e64 v26, -1, v26, s[2:3]
	v_add_f32_e32 v27, 0, v27
	v_cmp_ge_u32_e64 s[4:5], s8, v182
	v_ashrrev_i32_e32 v121, 31, v27
	v_or_b32_e32 v121, 0x80000000, v121
	v_xnor_b32_e32 v27, v121, v27
	v_cndmask_b32_e64 v27, -1, v27, s[4:5]
	s_cmp_le_u32 s9, 28
	s_cbranch_scc1 .Ltk_cv_end
	v_add_f32_e32 v28, 0, v28
	v_cmp_ge_u32_e64 s[2:3], s8, v183
	v_ashrrev_i32_e32 v120, 31, v28
	v_or_b32_e32 v120, 0x80000000, v120
	v_xnor_b32_e32 v28, v120, v28
	v_cndmask_b32_e64 v28, -1, v28, s[2:3]
	v_add_f32_e32 v29, 0, v29
	v_cmp_ge_u32_e64 s[4:5], s8, v184
	v_ashrrev_i32_e32 v121, 31, v29
	v_or_b32_e32 v121, 0x80000000, v121
	v_xnor_b32_e32 v29, v121, v29
	v_cndmask_b32_e64 v29, -1, v29, s[4:5]
	v_add_f32_e32 v30, 0, v30
	v_cmp_ge_u32_e64 s[2:3], s8, v185
	v_ashrrev_i32_e32 v120, 31, v30
	v_or_b32_e32 v120, 0x80000000, v120
	v_xnor_b32_e32 v30, v120, v30
	v_cndmask_b32_e64 v30, -1, v30, s[2:3]
	v_add_f32_e32 v31, 0, v31
	v_cmp_ge_u32_e64 s[4:5], s8, v186
	v_ashrrev_i32_e32 v121, 31, v31
	v_or_b32_e32 v121, 0x80000000, v121
	v_xnor_b32_e32 v31, v121, v31
	v_cndmask_b32_e64 v31, -1, v31, s[4:5]
.Ltk_cv_end:
	s_mov_b32 s33, 0
	s_movk_i32 s82, 0x100
	s_mov_b32 s11, 24
	ds_write_b128 v190, v[242:245]
	v_lshrrev_b32_e32 v120, 24, v0
	v_lshl_add_u32 v120, v120, 2, v155
	ds_add_u32 v120, v227
	v_lshrrev_b32_e32 v121, 24, v1
	v_lshl_add_u32 v121, v121, 2, v155
	ds_add_u32 v121, v227
	v_lshrrev_b32_e32 v120, 24, v2
	v_lshl_add_u32 v120, v120, 2, v155
	ds_add_u32 v120, v227
	v_lshrrev_b32_e32 v121, 24, v3
	v_lshl_add_u32 v121, v121, 2, v155
	ds_add_u32 v121, v227
	s_cmp_le_u32 s9, 4
	s_cbranch_scc1 .Ltk_scan
	v_lshrrev_b32_e32 v120, 24, v4
	v_lshl_add_u32 v120, v120, 2, v155
	ds_add_u32 v120, v227
	v_lshrrev_b32_e32 v121, 24, v5
	v_lshl_add_u32 v121, v121, 2, v155
	ds_add_u32 v121, v227
	v_lshrrev_b32_e32 v120, 24, v6
	v_lshl_add_u32 v120, v120, 2, v155
	ds_add_u32 v120, v227
	v_lshrrev_b32_e32 v121, 24, v7
	v_lshl_add_u32 v121, v121, 2, v155
	ds_add_u32 v121, v227
	s_cmp_le_u32 s9, 8
	s_cbranch_scc1 .Ltk_scan
	v_lshrrev_b32_e32 v120, 24, v8
	v_lshl_add_u32 v120, v120, 2, v155
	ds_add_u32 v120, v227
	v_lshrrev_b32_e32 v121, 24, v9
	v_lshl_add_u32 v121, v121, 2, v155
	ds_add_u32 v121, v227
	v_lshrrev_b32_e32 v120, 24, v10
	v_lshl_add_u32 v120, v120, 2, v155
	ds_add_u32 v120, v227
	v_lshrrev_b32_e32 v121, 24, v11
	v_lshl_add_u32 v121, v121, 2, v155
	ds_add_u32 v121, v227
	s_cmp_le_u32 s9, 12
	s_cbranch_scc1 .Ltk_scan
	v_lshrrev_b32_e32 v120, 24, v12
	v_lshl_add_u32 v120, v120, 2, v155
	ds_add_u32 v120, v227
	v_lshrrev_b32_e32 v121, 24, v13
	v_lshl_add_u32 v121, v121, 2, v155
	ds_add_u32 v121, v227
	v_lshrrev_b32_e32 v120, 24, v14
	v_lshl_add_u32 v120, v120, 2, v155
	ds_add_u32 v120, v227
	v_lshrrev_b32_e32 v121, 24, v15
	v_lshl_add_u32 v121, v121, 2, v155
	ds_add_u32 v121, v227
	s_cmp_le_u32 s9, 16
	s_cbranch_scc1 .Ltk_scan
	v_lshrrev_b32_e32 v120, 24, v16
	v_lshl_add_u32 v120, v120, 2, v155
	ds_add_u32 v120, v227
	v_lshrrev_b32_e32 v121, 24, v17
	v_lshl_add_u32 v121, v121, 2, v155
	ds_add_u32 v121, v227
	v_lshrrev_b32_e32 v120, 24, v18
	v_lshl_add_u32 v120, v120, 2, v155
	ds_add_u32 v120, v227
	v_lshrrev_b32_e32 v121, 24, v19
	v_lshl_add_u32 v121, v121, 2, v155
	ds_add_u32 v121, v227
	s_cmp_le_u32 s9, 20
	s_cbranch_scc1 .Ltk_scan
	v_lshrrev_b32_e32 v120, 24, v20
	v_lshl_add_u32 v120, v120, 2, v155
	ds_add_u32 v120, v227
	v_lshrrev_b32_e32 v121, 24, v21
	v_lshl_add_u32 v121, v121, 2, v155
	ds_add_u32 v121, v227
	v_lshrrev_b32_e32 v120, 24, v22
	v_lshl_add_u32 v120, v120, 2, v155
	ds_add_u32 v120, v227
	v_lshrrev_b32_e32 v121, 24, v23
	v_lshl_add_u32 v121, v121, 2, v155
	ds_add_u32 v121, v227
	s_cmp_le_u32 s9, 24
	s_cbranch_scc1 .Ltk_scan
	v_lshrrev_b32_e32 v120, 24, v24
	v_lshl_add_u32 v120, v120, 2, v155
	ds_add_u32 v120, v227
	v_lshrrev_b32_e32 v121, 24, v25
	v_lshl_add_u32 v121, v121, 2, v155
	ds_add_u32 v121, v227
	v_lshrrev_b32_e32 v120, 24, v26
	v_lshl_add_u32 v120, v120, 2, v155
	ds_add_u32 v120, v227
	v_lshrrev_b32_e32 v121, 24, v27
	v_lshl_add_u32 v121, v121, 2, v155
	ds_add_u32 v121, v227
	s_cmp_le_u32 s9, 28
	s_cbranch_scc1 .Ltk_scan
	v_lshrrev_b32_e32 v120, 24, v28
	v_lshl_add_u32 v120, v120, 2, v155
	ds_add_u32 v120, v227
	v_lshrrev_b32_e32 v121, 24, v29
	v_lshl_add_u32 v121, v121, 2, v155
	ds_add_u32 v121, v227
	v_lshrrev_b32_e32 v120, 24, v30
	v_lshl_add_u32 v120, v120, 2, v155
	ds_add_u32 v120, v227
	v_lshrrev_b32_e32 v121, 24, v31
	v_lshl_add_u32 v121, v121, 2, v155
	ds_add_u32 v121, v227
	s_branch .Ltk_scan
; __device__ __forceinline__ void dsa_index_phase(const Params& p, unsigned char* smem) {
;     ...
;                 for (int pass = 0; pass < 4; ++pass) {
;                     const int shift = 24 - 8 * pass;
;                     const unsigned hmask = pass == 0 ? 0u : (0xFFFFFFFFu << (shift + 8));
;                     *(u32x4*)(H + lane * 4) = (u32x4){0u, 0u, 0u, 0u};
;                     asm volatile("s_waitcnt lgkmcnt(0)" ::: "memory");
; #pragma unroll
;                     for (int i = 0; i < 32; ++i) if (i < ni) { const unsigned uu = u[i]; if (uu != 0u && (uu & hmask) == prefix) atomicAdd(H + ((uu >> shift) & 255u), 1u); }
;                     asm volatile("s_waitcnt lgkmcnt(0)" ::: "memory");
.Ltk_pass:
	s_add_i32 s7, s11, 8
	s_lshl_b32 s10, 1, s7
	ds_write_b128 v190, v[242:245]
	v_xor_b32_e32 v120, s33, v0
	v_cmp_gt_u32_e32 vcc, s10, v120
	s_cbranch_vccz .Ltk_m0
	v_bfe_u32 v121, v0, s11, 8
	v_lshl_add_u32 v121, v121, 2, v155
	s_and_saveexec_b64 s[2:3], vcc
	ds_add_u32 v121, v227
	s_or_b64 exec, exec, s[2:3]
.Ltk_m0:
	v_xor_b32_e32 v120, s33, v1
	v_cmp_gt_u32_e32 vcc, s10, v120
	s_cbranch_vccz .Ltk_m1
	v_bfe_u32 v121, v1, s11, 8
	v_lshl_add_u32 v121, v121, 2, v155
	s_and_saveexec_b64 s[2:3], vcc
	ds_add_u32 v121, v227
	s_or_b64 exec, exec, s[2:3]
.Ltk_m1:
	v_xor_b32_e32 v120, s33, v2
	v_cmp_gt_u32_e32 vcc, s10, v120
	s_cbranch_vccz .Ltk_m2
	v_bfe_u32 v121, v2, s11, 8
	v_lshl_add_u32 v121, v121, 2, v155
	s_and_saveexec_b64 s[2:3], vcc
	ds_add_u32 v121, v227
	s_or_b64 exec, exec, s[2:3]
.Ltk_m2:
	v_xor_b32_e32 v120, s33, v3
	v_cmp_gt_u32_e32 vcc, s10, v120
	s_cbranch_vccz .Ltk_m3
	v_bfe_u32 v121, v3, s11, 8
	v_lshl_add_u32 v121, v121, 2, v155
	s_and_saveexec_b64 s[2:3], vcc
	ds_add_u32 v121, v227
	s_or_b64 exec, exec, s[2:3]
.Ltk_m3:
	s_cmp_le_u32 s9, 4
	s_cbranch_scc1 .Ltk_scan
	v_xor_b32_e32 v120, s33, v4
	v_cmp_gt_u32_e32 vcc, s10, v120
	s_cbranch_vccz .Ltk_m4
	v_bfe_u32 v121, v4, s11, 8
	v_lshl_add_u32 v121, v121, 2, v155
	s_and_saveexec_b64 s[2:3], vcc
	ds_add_u32 v121, v227
	s_or_b64 exec, exec, s[2:3]
.Ltk_m4:
	v_xor_b32_e32 v120, s33, v5
	v_cmp_gt_u32_e32 vcc, s10, v120
	s_cbranch_vccz .Ltk_m5
	v_bfe_u32 v121, v5, s11, 8
	v_lshl_add_u32 v121, v121, 2, v155
	s_and_saveexec_b64 s[2:3], vcc
	ds_add_u32 v121, v227
	s_or_b64 exec, exec, s[2:3]
.Ltk_m5:
	v_xor_b32_e32 v120, s33, v6
	v_cmp_gt_u32_e32 vcc, s10, v120
	s_cbranch_vccz .Ltk_m6
	v_bfe_u32 v121, v6, s11, 8
	v_lshl_add_u32 v121, v121, 2, v155
	s_and_saveexec_b64 s[2:3], vcc
	ds_add_u32 v121, v227
	s_or_b64 exec, exec, s[2:3]
.Ltk_m6:
	v_xor_b32_e32 v120, s33, v7
	v_cmp_gt_u32_e32 vcc, s10, v120
	s_cbranch_vccz .Ltk_m7
	v_bfe_u32 v121, v7, s11, 8
	v_lshl_add_u32 v121, v121, 2, v155
	s_and_saveexec_b64 s[2:3], vcc
	ds_add_u32 v121, v227
	s_or_b64 exec, exec, s[2:3]
.Ltk_m7:
	s_cmp_le_u32 s9, 8
	s_cbranch_scc1 .Ltk_scan
	v_xor_b32_e32 v120, s33, v8
	v_cmp_gt_u32_e32 vcc, s10, v120
	s_cbranch_vccz .Ltk_m8
	v_bfe_u32 v121, v8, s11, 8
	v_lshl_add_u32 v121, v121, 2, v155
	s_and_saveexec_b64 s[2:3], vcc
	ds_add_u32 v121, v227
	s_or_b64 exec, exec, s[2:3]
.Ltk_m8:
	v_xor_b32_e32 v120, s33, v9
	v_cmp_gt_u32_e32 vcc, s10, v120
	s_cbranch_vccz .Ltk_m9
	v_bfe_u32 v121, v9, s11, 8
	v_lshl_add_u32 v121, v121, 2, v155
	s_and_saveexec_b64 s[2:3], vcc
	ds_add_u32 v121, v227
	s_or_b64 exec, exec, s[2:3]
.Ltk_m9:
	v_xor_b32_e32 v120, s33, v10
	v_cmp_gt_u32_e32 vcc, s10, v120
	s_cbranch_vccz .Ltk_m10
	v_bfe_u32 v121, v10, s11, 8
	v_lshl_add_u32 v121, v121, 2, v155
	s_and_saveexec_b64 s[2:3], vcc
	ds_add_u32 v121, v227
	s_or_b64 exec, exec, s[2:3]
.Ltk_m10:
	v_xor_b32_e32 v120, s33, v11
	v_cmp_gt_u32_e32 vcc, s10, v120
	s_cbranch_vccz .Ltk_m11
	v_bfe_u32 v121, v11, s11, 8
	v_lshl_add_u32 v121, v121, 2, v155
	s_and_saveexec_b64 s[2:3], vcc
	ds_add_u32 v121, v227
	s_or_b64 exec, exec, s[2:3]
.Ltk_m11:
	s_cmp_le_u32 s9, 12
	s_cbranch_scc1 .Ltk_scan
	v_xor_b32_e32 v120, s33, v12
	v_cmp_gt_u32_e32 vcc, s10, v120
	s_cbranch_vccz .Ltk_m12
	v_bfe_u32 v121, v12, s11, 8
	v_lshl_add_u32 v121, v121, 2, v155
	s_and_saveexec_b64 s[2:3], vcc
	ds_add_u32 v121, v227
	s_or_b64 exec, exec, s[2:3]
.Ltk_m12:
	v_xor_b32_e32 v120, s33, v13
	v_cmp_gt_u32_e32 vcc, s10, v120
	s_cbranch_vccz .Ltk_m13
	v_bfe_u32 v121, v13, s11, 8
	v_lshl_add_u32 v121, v121, 2, v155
	s_and_saveexec_b64 s[2:3], vcc
	ds_add_u32 v121, v227
	s_or_b64 exec, exec, s[2:3]
.Ltk_m13:
	v_xor_b32_e32 v120, s33, v14
	v_cmp_gt_u32_e32 vcc, s10, v120
	s_cbranch_vccz .Ltk_m14
	v_bfe_u32 v121, v14, s11, 8
	v_lshl_add_u32 v121, v121, 2, v155
	s_and_saveexec_b64 s[2:3], vcc
	ds_add_u32 v121, v227
	s_or_b64 exec, exec, s[2:3]
.Ltk_m14:
	v_xor_b32_e32 v120, s33, v15
	v_cmp_gt_u32_e32 vcc, s10, v120
	s_cbranch_vccz .Ltk_m15
	v_bfe_u32 v121, v15, s11, 8
	v_lshl_add_u32 v121, v121, 2, v155
	s_and_saveexec_b64 s[2:3], vcc
	ds_add_u32 v121, v227
	s_or_b64 exec, exec, s[2:3]
.Ltk_m15:
	s_cmp_le_u32 s9, 16
	s_cbranch_scc1 .Ltk_scan
	v_xor_b32_e32 v120, s33, v16
	v_cmp_gt_u32_e32 vcc, s10, v120
	s_cbranch_vccz .Ltk_m16
	v_bfe_u32 v121, v16, s11, 8
	v_lshl_add_u32 v121, v121, 2, v155
	s_and_saveexec_b64 s[2:3], vcc
	ds_add_u32 v121, v227
	s_or_b64 exec, exec, s[2:3]
.Ltk_m16:
	v_xor_b32_e32 v120, s33, v17
	v_cmp_gt_u32_e32 vcc, s10, v120
	s_cbranch_vccz .Ltk_m17
	v_bfe_u32 v121, v17, s11, 8
	v_lshl_add_u32 v121, v121, 2, v155
	s_and_saveexec_b64 s[2:3], vcc
	ds_add_u32 v121, v227
	s_or_b64 exec, exec, s[2:3]
.Ltk_m17:
	v_xor_b32_e32 v120, s33, v18
	v_cmp_gt_u32_e32 vcc, s10, v120
	s_cbranch_vccz .Ltk_m18
	v_bfe_u32 v121, v18, s11, 8
	v_lshl_add_u32 v121, v121, 2, v155
	s_and_saveexec_b64 s[2:3], vcc
	ds_add_u32 v121, v227
	s_or_b64 exec, exec, s[2:3]
.Ltk_m18:
	v_xor_b32_e32 v120, s33, v19
	v_cmp_gt_u32_e32 vcc, s10, v120
	s_cbranch_vccz .Ltk_m19
	v_bfe_u32 v121, v19, s11, 8
	v_lshl_add_u32 v121, v121, 2, v155
	s_and_saveexec_b64 s[2:3], vcc
	ds_add_u32 v121, v227
	s_or_b64 exec, exec, s[2:3]
.Ltk_m19:
	s_cmp_le_u32 s9, 20
	s_cbranch_scc1 .Ltk_scan
	v_xor_b32_e32 v120, s33, v20
	v_cmp_gt_u32_e32 vcc, s10, v120
	s_cbranch_vccz .Ltk_m20
	v_bfe_u32 v121, v20, s11, 8
	v_lshl_add_u32 v121, v121, 2, v155
	s_and_saveexec_b64 s[2:3], vcc
	ds_add_u32 v121, v227
	s_or_b64 exec, exec, s[2:3]
.Ltk_m20:
	v_xor_b32_e32 v120, s33, v21
	v_cmp_gt_u32_e32 vcc, s10, v120
	s_cbranch_vccz .Ltk_m21
	v_bfe_u32 v121, v21, s11, 8
	v_lshl_add_u32 v121, v121, 2, v155
	s_and_saveexec_b64 s[2:3], vcc
	ds_add_u32 v121, v227
	s_or_b64 exec, exec, s[2:3]
; __device__ __forceinline__ void dsa_index_phase(const Params& p, unsigned char* smem) {
;     ...
;                     for (int i = 0; i < 32; ++i) if (i < ni) { const unsigned uu = u[i]; if (uu != 0u && (uu & hmask) == prefix) atomicAdd(H + ((uu >> shift) & 255u), 1u); }
;                     asm volatile("s_waitcnt lgkmcnt(0)" ::: "memory");
;                     const u32x4 hv = *(const u32x4*)(H + lane * 4);
;                     const int tot = (int)(hv.x + hv.y + hv.z + hv.w);
;                     int rs = tot;
;                     rs += __builtin_amdgcn_update_dpp(0, rs, 0xB1, 0xF, 0xF, true);
;                     rs += __builtin_amdgcn_update_dpp(0, rs, 0x4E, 0xF, 0xF, true);
;                     rs += __builtin_amdgcn_update_dpp(0, rs, 0x141, 0xF, 0xF, true);
;                     rs += __builtin_amdgcn_update_dpp(0, rs, 0x140, 0xF, 0xF, true);
;                     int rowsel = 3, above = 0;
;                     {
;                         const int r3 = __builtin_amdgcn_readlane(rs, 48), r2 = __builtin_amdgcn_readlane(rs, 32), r1 = __builtin_amdgcn_readlane(rs, 16);
;                         if (need > r3) { above = r3; rowsel = 2; if (need > above + r2) { above += r2; rowsel = 1; if (need > above + r1) { above += r1; rowsel = 0; } } }
;                     }
;                     int lsel = rowsel * 16;
;                     for (int k = 15; k >= 0; --k) {
;                         const int cl = __builtin_amdgcn_readlane(tot, rowsel * 16 + k);
;                         if (need <= above + cl) { lsel = rowsel * 16 + k; break; }
;                         above += cl;
;                     }
;                     const int b3 = __builtin_amdgcn_readlane((int)hv.w, lsel), b2 = __builtin_amdgcn_readlane((int)hv.z, lsel), b1 = __builtin_amdgcn_readlane((int)hv.y, lsel);
;                     int bsel = 3;
;                     if (need > above + b3) { above += b3; bsel = 2; if (need > above + b2) { above += b2; bsel = 1; if (need > above + b1) { above += b1; bsel = 0; } } }
;                     prefix |= (unsigned)(lsel * 4 + bsel) << shift;
;                     need -= above;
;                 }
;                 const unsigned T = prefix;
;                 int running = 0, outpos = 0;
;                 const unsigned long long lt = (lane == 0) ? 0ull : (~0ull >> (64 - lane));
; #pragma unroll
;                 for (int i = 0; i < 32; ++i) {
.Ltk_m21:
	v_xor_b32_e32 v120, s33, v22
	v_cmp_gt_u32_e32 vcc, s10, v120
	s_cbranch_vccz .Ltk_m22
	v_bfe_u32 v121, v22, s11, 8
	v_lshl_add_u32 v121, v121, 2, v155
	s_and_saveexec_b64 s[2:3], vcc
	ds_add_u32 v121, v227
	s_or_b64 exec, exec, s[2:3]
.Ltk_m22:
	v_xor_b32_e32 v120, s33, v23
	v_cmp_gt_u32_e32 vcc, s10, v120
	s_cbranch_vccz .Ltk_m23
	v_bfe_u32 v121, v23, s11, 8
	v_lshl_add_u32 v121, v121, 2, v155
	s_and_saveexec_b64 s[2:3], vcc
	ds_add_u32 v121, v227
	s_or_b64 exec, exec, s[2:3]
.Ltk_m23:
	s_cmp_le_u32 s9, 24
	s_cbranch_scc1 .Ltk_scan
	v_xor_b32_e32 v120, s33, v24
	v_cmp_gt_u32_e32 vcc, s10, v120
	s_cbranch_vccz .Ltk_m24
	v_bfe_u32 v121, v24, s11, 8
	v_lshl_add_u32 v121, v121, 2, v155
	s_and_saveexec_b64 s[2:3], vcc
	ds_add_u32 v121, v227
	s_or_b64 exec, exec, s[2:3]
.Ltk_m24:
	v_xor_b32_e32 v120, s33, v25
	v_cmp_gt_u32_e32 vcc, s10, v120
	s_cbranch_vccz .Ltk_m25
	v_bfe_u32 v121, v25, s11, 8
	v_lshl_add_u32 v121, v121, 2, v155
	s_and_saveexec_b64 s[2:3], vcc
	ds_add_u32 v121, v227
	s_or_b64 exec, exec, s[2:3]
.Ltk_m25:
	v_xor_b32_e32 v120, s33, v26
	v_cmp_gt_u32_e32 vcc, s10, v120
	s_cbranch_vccz .Ltk_m26
	v_bfe_u32 v121, v26, s11, 8
	v_lshl_add_u32 v121, v121, 2, v155
	s_and_saveexec_b64 s[2:3], vcc
	ds_add_u32 v121, v227
	s_or_b64 exec, exec, s[2:3]
.Ltk_m26:
	v_xor_b32_e32 v120, s33, v27
	v_cmp_gt_u32_e32 vcc, s10, v120
	s_cbranch_vccz .Ltk_m27
	v_bfe_u32 v121, v27, s11, 8
	v_lshl_add_u32 v121, v121, 2, v155
	s_and_saveexec_b64 s[2:3], vcc
	ds_add_u32 v121, v227
	s_or_b64 exec, exec, s[2:3]
.Ltk_m27:
	s_cmp_le_u32 s9, 28
	s_cbranch_scc1 .Ltk_scan
	v_xor_b32_e32 v120, s33, v28
	v_cmp_gt_u32_e32 vcc, s10, v120
	s_cbranch_vccz .Ltk_m28
	v_bfe_u32 v121, v28, s11, 8
	v_lshl_add_u32 v121, v121, 2, v155
	s_and_saveexec_b64 s[2:3], vcc
	ds_add_u32 v121, v227
	s_or_b64 exec, exec, s[2:3]
.Ltk_m28:
	v_xor_b32_e32 v120, s33, v29
	v_cmp_gt_u32_e32 vcc, s10, v120
	s_cbranch_vccz .Ltk_m29
	v_bfe_u32 v121, v29, s11, 8
	v_lshl_add_u32 v121, v121, 2, v155
	s_and_saveexec_b64 s[2:3], vcc
	ds_add_u32 v121, v227
	s_or_b64 exec, exec, s[2:3]
.Ltk_m29:
	v_xor_b32_e32 v120, s33, v30
	v_cmp_gt_u32_e32 vcc, s10, v120
	s_cbranch_vccz .Ltk_m30
	v_bfe_u32 v121, v30, s11, 8
	v_lshl_add_u32 v121, v121, 2, v155
	s_and_saveexec_b64 s[2:3], vcc
	ds_add_u32 v121, v227
	s_or_b64 exec, exec, s[2:3]
.Ltk_m30:
	v_xor_b32_e32 v120, s33, v31
	v_cmp_gt_u32_e32 vcc, s10, v120
	s_cbranch_vccz .Ltk_m31
	v_bfe_u32 v121, v31, s11, 8
	v_lshl_add_u32 v121, v121, 2, v155
	s_and_saveexec_b64 s[2:3], vcc
	ds_add_u32 v121, v227
	s_or_b64 exec, exec, s[2:3]
.Ltk_m31:
.Ltk_scan:
	ds_read_b128 v[132:135], v190
	s_waitcnt lgkmcnt(0)
	v_add_u32_e32 v136, v132, v133
	v_add_u32_e32 v137, v134, v135
	v_add_u32_e32 v136, v136, v137
	v_mov_b32_e32 v137, v136
	s_nop 1
	v_add_u32_dpp v137, v137, v137 row_shr:1 row_mask:0xf bank_mask:0xf bound_ctrl:1
	s_nop 1
	v_add_u32_dpp v137, v137, v137 row_shr:2 row_mask:0xf bank_mask:0xf bound_ctrl:1
	s_nop 1
	v_add_u32_dpp v137, v137, v137 row_shr:4 row_mask:0xf bank_mask:0xf bound_ctrl:1
	s_nop 1
	v_add_u32_dpp v137, v137, v137 row_shr:8 row_mask:0xf bank_mask:0xf bound_ctrl:1
	s_nop 1
	v_add_u32_dpp v137, v137, v137 row_bcast:15 row_mask:0xa bank_mask:0xf
	s_nop 1
	v_add_u32_dpp v137, v137, v137 row_bcast:31 row_mask:0xc bank_mask:0xf
	s_nop 1
	v_cmp_le_u32_e64 s[2:3], s82, v137
	s_ff1_i32_b64 s16, s[2:3]
	v_readlane_b32 s17, v137, s16
	v_readlane_b32 s6, v136, s16
	v_readlane_b32 s0, v132, s16
	v_readlane_b32 s1, v133, s16
	v_readlane_b32 s2, v134, s16
	s_sub_u32 s17, s17, s6
	s_add_u32 s0, s17, s0
	s_add_u32 s1, s0, s1
	s_add_u32 s2, s1, s2
	s_mov_b32 s3, 0
	s_cmp_gt_u32 s82, s0
	s_cselect_b32 s17, s0, s17
	s_addc_u32 s3, s3, 0
	s_cmp_gt_u32 s82, s1
	s_cselect_b32 s17, s1, s17
	s_addc_u32 s3, s3, 0
	s_cmp_gt_u32 s82, s2
	s_cselect_b32 s17, s2, s17
	s_addc_u32 s3, s3, 0
	s_lshl_b32 s16, s16, 2
	s_add_u32 s16, s16, s3
	s_lshl_b32 s16, s16, s11
	s_or_b32 s33, s33, s16
	s_sub_u32 s82, s82, s17
	s_cmp_eq_u32 s11, 0
	s_cbranch_scc1 .Ltk_compact
	s_sub_u32 s11, s11, 8
	s_branch .Ltk_pass
.Ltk_compact:
	s_mov_b32 s14, 0
	v_cmp_gt_u32_e64 s[4:5], s33, v0
	v_cmp_eq_u32_e32 vcc, s33, v0
	s_cbranch_vccz .Ltk_c0
	s_bcnt1_i32_b64 s7, vcc
	v_mbcnt_lo_u32_b32 v121, vcc_lo, 0
	v_mbcnt_hi_u32_b32 v121, vcc_hi, v121
	v_cmp_gt_u32_e64 s[2:3], s82, v121
	s_sub_i32 s82, s82, s7
	s_max_i32 s82, s82, 0
	s_and_b64 s[2:3], s[2:3], vcc
	s_or_b64 s[4:5], s[4:5], s[2:3]
.Ltk_c0:
	s_bcnt1_i32_b64 s6, s[4:5]
	v_mbcnt_lo_u32_b32 v120, s4, 0
	v_mbcnt_hi_u32_b32 v120, s5, v120
	v_add_lshl_u32 v120, v120, s14, 1
	s_mov_b64 exec, s[4:5]
	global_store_short v120, v124, s[12:13]
	s_mov_b64 exec, -1
	s_add_u32 s14, s14, s6
	v_cmp_gt_u32_e64 s[4:5], s33, v1
	v_cmp_eq_u32_e32 vcc, s33, v1
	s_cbranch_vccz .Ltk_c1
	s_bcnt1_i32_b64 s7, vcc
	v_mbcnt_lo_u32_b32 v121, vcc_lo, 0
	v_mbcnt_hi_u32_b32 v121, vcc_hi, v121
	v_cmp_gt_u32_e64 s[2:3], s82, v121
	s_sub_i32 s82, s82, s7
	s_max_i32 s82, s82, 0
	s_and_b64 s[2:3], s[2:3], vcc
	s_or_b64 s[4:5], s[4:5], s[2:3]
.Ltk_c1:
	s_bcnt1_i32_b64 s6, s[4:5]
	v_mbcnt_lo_u32_b32 v120, s4, 0
	v_mbcnt_hi_u32_b32 v120, s5, v120
	v_add_lshl_u32 v120, v120, s14, 1
	s_mov_b64 exec, s[4:5]
	global_store_short v120, v156, s[12:13]
	s_mov_b64 exec, -1
	s_add_u32 s14, s14, s6
	v_cmp_gt_u32_e64 s[4:5], s33, v2
	v_cmp_eq_u32_e32 vcc, s33, v2
	s_cbranch_vccz .Ltk_c2
	s_bcnt1_i32_b64 s7, vcc
	v_mbcnt_lo_u32_b32 v121, vcc_lo, 0
	v_mbcnt_hi_u32_b32 v121, vcc_hi, v121
	v_cmp_gt_u32_e64 s[2:3], s82, v121
	s_sub_i32 s82, s82, s7
	s_max_i32 s82, s82, 0
	s_and_b64 s[2:3], s[2:3], vcc
	s_or_b64 s[4:5], s[4:5], s[2:3]
; __device__ __forceinline__ void dsa_index_phase(const Params& p, unsigned char* smem) {
;     ...
;                 const unsigned T = prefix;
;                 int running = 0, outpos = 0;
;                 const unsigned long long lt = (lane == 0) ? 0ull : (~0ull >> (64 - lane));
; #pragma unroll
;                 for (int i = 0; i < 32; ++i) {
;                     if (i < ni) {
;                         const unsigned long long eq = __ballot(u[i] == T);
;                         const int rank = running + __popcll(eq & lt);
;                         const bool sel = u[i] > T || (u[i] == T && rank < need);
;                         const unsigned long long sm = __ballot(sel);
;                         running += __popcll(eq);
;                         if (sel) selrow[outpos + __popcll(sm & lt)] = (unsigned short)(i * 64 + lane);
;                         outpos += __popcll(sm);
;                     }
.Ltk_c2:
	s_bcnt1_i32_b64 s6, s[4:5]
	v_mbcnt_lo_u32_b32 v120, s4, 0
	v_mbcnt_hi_u32_b32 v120, s5, v120
	v_add_lshl_u32 v120, v120, s14, 1
	s_mov_b64 exec, s[4:5]
	global_store_short v120, v157, s[12:13]
	s_mov_b64 exec, -1
	s_add_u32 s14, s14, s6
	v_cmp_gt_u32_e64 s[4:5], s33, v3
	v_cmp_eq_u32_e32 vcc, s33, v3
	s_cbranch_vccz .Ltk_c3
	s_bcnt1_i32_b64 s7, vcc
	v_mbcnt_lo_u32_b32 v121, vcc_lo, 0
	v_mbcnt_hi_u32_b32 v121, vcc_hi, v121
	v_cmp_gt_u32_e64 s[2:3], s82, v121
	s_sub_i32 s82, s82, s7
	s_max_i32 s82, s82, 0
	s_and_b64 s[2:3], s[2:3], vcc
	s_or_b64 s[4:5], s[4:5], s[2:3]
.Ltk_c3:
	s_bcnt1_i32_b64 s6, s[4:5]
	v_mbcnt_lo_u32_b32 v120, s4, 0
	v_mbcnt_hi_u32_b32 v120, s5, v120
	v_add_lshl_u32 v120, v120, s14, 1
	s_mov_b64 exec, s[4:5]
	global_store_short v120, v158, s[12:13]
	s_mov_b64 exec, -1
	s_add_u32 s14, s14, s6
	s_cmp_le_u32 s9, 4
	s_cbranch_scc1 .Ltk_done
	v_cmp_gt_u32_e64 s[4:5], s33, v4
	v_cmp_eq_u32_e32 vcc, s33, v4
	s_cbranch_vccz .Ltk_c4
	s_bcnt1_i32_b64 s7, vcc
	v_mbcnt_lo_u32_b32 v121, vcc_lo, 0
	v_mbcnt_hi_u32_b32 v121, vcc_hi, v121
	v_cmp_gt_u32_e64 s[2:3], s82, v121
	s_sub_i32 s82, s82, s7
	s_max_i32 s82, s82, 0
	s_and_b64 s[2:3], s[2:3], vcc
	s_or_b64 s[4:5], s[4:5], s[2:3]
.Ltk_c4:
	s_bcnt1_i32_b64 s6, s[4:5]
	v_mbcnt_lo_u32_b32 v120, s4, 0
	v_mbcnt_hi_u32_b32 v120, s5, v120
	v_add_lshl_u32 v120, v120, s14, 1
	s_mov_b64 exec, s[4:5]
	global_store_short v120, v159, s[12:13]
	s_mov_b64 exec, -1
	s_add_u32 s14, s14, s6
	v_cmp_gt_u32_e64 s[4:5], s33, v5
	v_cmp_eq_u32_e32 vcc, s33, v5
	s_cbranch_vccz .Ltk_c5
	s_bcnt1_i32_b64 s7, vcc
	v_mbcnt_lo_u32_b32 v121, vcc_lo, 0
	v_mbcnt_hi_u32_b32 v121, vcc_hi, v121
	v_cmp_gt_u32_e64 s[2:3], s82, v121
	s_sub_i32 s82, s82, s7
	s_max_i32 s82, s82, 0
	s_and_b64 s[2:3], s[2:3], vcc
	s_or_b64 s[4:5], s[4:5], s[2:3]
.Ltk_c5:
	s_bcnt1_i32_b64 s6, s[4:5]
	v_mbcnt_lo_u32_b32 v120, s4, 0
	v_mbcnt_hi_u32_b32 v120, s5, v120
	v_add_lshl_u32 v120, v120, s14, 1
	s_mov_b64 exec, s[4:5]
	global_store_short v120, v160, s[12:13]
	s_mov_b64 exec, -1
	s_add_u32 s14, s14, s6
	v_cmp_gt_u32_e64 s[4:5], s33, v6
	v_cmp_eq_u32_e32 vcc, s33, v6
	s_cbranch_vccz .Ltk_c6
	s_bcnt1_i32_b64 s7, vcc
	v_mbcnt_lo_u32_b32 v121, vcc_lo, 0
	v_mbcnt_hi_u32_b32 v121, vcc_hi, v121
	v_cmp_gt_u32_e64 s[2:3], s82, v121
	s_sub_i32 s82, s82, s7
	s_max_i32 s82, s82, 0
	s_and_b64 s[2:3], s[2:3], vcc
	s_or_b64 s[4:5], s[4:5], s[2:3]
.Ltk_c6:
	s_bcnt1_i32_b64 s6, s[4:5]
	v_mbcnt_lo_u32_b32 v120, s4, 0
	v_mbcnt_hi_u32_b32 v120, s5, v120
	v_add_lshl_u32 v120, v120, s14, 1
	s_mov_b64 exec, s[4:5]
	global_store_short v120, v161, s[12:13]
	s_mov_b64 exec, -1
	s_add_u32 s14, s14, s6
	v_cmp_gt_u32_e64 s[4:5], s33, v7
	v_cmp_eq_u32_e32 vcc, s33, v7
	s_cbranch_vccz .Ltk_c7
	s_bcnt1_i32_b64 s7, vcc
	v_mbcnt_lo_u32_b32 v121, vcc_lo, 0
	v_mbcnt_hi_u32_b32 v121, vcc_hi, v121
	v_cmp_gt_u32_e64 s[2:3], s82, v121
	s_sub_i32 s82, s82, s7
	s_max_i32 s82, s82, 0
	s_and_b64 s[2:3], s[2:3], vcc
	s_or_b64 s[4:5], s[4:5], s[2:3]
.Ltk_c7:
	s_bcnt1_i32_b64 s6, s[4:5]
	v_mbcnt_lo_u32_b32 v120, s4, 0
	v_mbcnt_hi_u32_b32 v120, s5, v120
	v_add_lshl_u32 v120, v120, s14, 1
	s_mov_b64 exec, s[4:5]
	global_store_short v120, v162, s[12:13]
	s_mov_b64 exec, -1
	s_add_u32 s14, s14, s6
	s_cmp_le_u32 s9, 8
	s_cbranch_scc1 .Ltk_done
	v_cmp_gt_u32_e64 s[4:5], s33, v8
	v_cmp_eq_u32_e32 vcc, s33, v8
	s_cbranch_vccz .Ltk_c8
	s_bcnt1_i32_b64 s7, vcc
	v_mbcnt_lo_u32_b32 v121, vcc_lo, 0
	v_mbcnt_hi_u32_b32 v121, vcc_hi, v121
	v_cmp_gt_u32_e64 s[2:3], s82, v121
	s_sub_i32 s82, s82, s7
	s_max_i32 s82, s82, 0
	s_and_b64 s[2:3], s[2:3], vcc
	s_or_b64 s[4:5], s[4:5], s[2:3]
.Ltk_c8:
	s_bcnt1_i32_b64 s6, s[4:5]
	v_mbcnt_lo_u32_b32 v120, s4, 0
	v_mbcnt_hi_u32_b32 v120, s5, v120
	v_add_lshl_u32 v120, v120, s14, 1
	s_mov_b64 exec, s[4:5]
	global_store_short v120, v163, s[12:13]
	s_mov_b64 exec, -1
	s_add_u32 s14, s14, s6
	v_cmp_gt_u32_e64 s[4:5], s33, v9
	v_cmp_eq_u32_e32 vcc, s33, v9
	s_cbranch_vccz .Ltk_c9
	s_bcnt1_i32_b64 s7, vcc
	v_mbcnt_lo_u32_b32 v121, vcc_lo, 0
	v_mbcnt_hi_u32_b32 v121, vcc_hi, v121
	v_cmp_gt_u32_e64 s[2:3], s82, v121
	s_sub_i32 s82, s82, s7
	s_max_i32 s82, s82, 0
	s_and_b64 s[2:3], s[2:3], vcc
	s_or_b64 s[4:5], s[4:5], s[2:3]
.Ltk_c9:
	s_bcnt1_i32_b64 s6, s[4:5]
	v_mbcnt_lo_u32_b32 v120, s4, 0
	v_mbcnt_hi_u32_b32 v120, s5, v120
	v_add_lshl_u32 v120, v120, s14, 1
	s_mov_b64 exec, s[4:5]
	global_store_short v120, v164, s[12:13]
	s_mov_b64 exec, -1
	s_add_u32 s14, s14, s6
	v_cmp_gt_u32_e64 s[4:5], s33, v10
	v_cmp_eq_u32_e32 vcc, s33, v10
	s_cbranch_vccz .Ltk_c10
	s_bcnt1_i32_b64 s7, vcc
	v_mbcnt_lo_u32_b32 v121, vcc_lo, 0
	v_mbcnt_hi_u32_b32 v121, vcc_hi, v121
	v_cmp_gt_u32_e64 s[2:3], s82, v121
	s_sub_i32 s82, s82, s7
	s_max_i32 s82, s82, 0
	s_and_b64 s[2:3], s[2:3], vcc
	s_or_b64 s[4:5], s[4:5], s[2:3]
.Ltk_c10:
	s_bcnt1_i32_b64 s6, s[4:5]
	v_mbcnt_lo_u32_b32 v120, s4, 0
	v_mbcnt_hi_u32_b32 v120, s5, v120
	v_add_lshl_u32 v120, v120, s14, 1
	s_mov_b64 exec, s[4:5]
	global_store_short v120, v165, s[12:13]
	s_mov_b64 exec, -1
	s_add_u32 s14, s14, s6
	v_cmp_gt_u32_e64 s[4:5], s33, v11
	v_cmp_eq_u32_e32 vcc, s33, v11
	s_cbranch_vccz .Ltk_c11
	s_bcnt1_i32_b64 s7, vcc
	v_mbcnt_lo_u32_b32 v121, vcc_lo, 0
	v_mbcnt_hi_u32_b32 v121, vcc_hi, v121
	v_cmp_gt_u32_e64 s[2:3], s82, v121
	s_sub_i32 s82, s82, s7
	s_max_i32 s82, s82, 0
	s_and_b64 s[2:3], s[2:3], vcc
	s_or_b64 s[4:5], s[4:5], s[2:3]
; __device__ __forceinline__ void dsa_index_phase(const Params& p, unsigned char* smem) {
;     ...
;                 const unsigned T = prefix;
;                 int running = 0, outpos = 0;
;                 const unsigned long long lt = (lane == 0) ? 0ull : (~0ull >> (64 - lane));
; #pragma unroll
;                 for (int i = 0; i < 32; ++i) {
;                     if (i < ni) {
;                         const unsigned long long eq = __ballot(u[i] == T);
;                         const int rank = running + __popcll(eq & lt);
;                         const bool sel = u[i] > T || (u[i] == T && rank < need);
;                         const unsigned long long sm = __ballot(sel);
;                         running += __popcll(eq);
;                         if (sel) selrow[outpos + __popcll(sm & lt)] = (unsigned short)(i * 64 + lane);
;                         outpos += __popcll(sm);
;                     }
.Ltk_c11:
	s_bcnt1_i32_b64 s6, s[4:5]
	v_mbcnt_lo_u32_b32 v120, s4, 0
	v_mbcnt_hi_u32_b32 v120, s5, v120
	v_add_lshl_u32 v120, v120, s14, 1
	s_mov_b64 exec, s[4:5]
	global_store_short v120, v166, s[12:13]
	s_mov_b64 exec, -1
	s_add_u32 s14, s14, s6
	s_cmp_le_u32 s9, 12
	s_cbranch_scc1 .Ltk_done
	v_cmp_gt_u32_e64 s[4:5], s33, v12
	v_cmp_eq_u32_e32 vcc, s33, v12
	s_cbranch_vccz .Ltk_c12
	s_bcnt1_i32_b64 s7, vcc
	v_mbcnt_lo_u32_b32 v121, vcc_lo, 0
	v_mbcnt_hi_u32_b32 v121, vcc_hi, v121
	v_cmp_gt_u32_e64 s[2:3], s82, v121
	s_sub_i32 s82, s82, s7
	s_max_i32 s82, s82, 0
	s_and_b64 s[2:3], s[2:3], vcc
	s_or_b64 s[4:5], s[4:5], s[2:3]
.Ltk_c12:
	s_bcnt1_i32_b64 s6, s[4:5]
	v_mbcnt_lo_u32_b32 v120, s4, 0
	v_mbcnt_hi_u32_b32 v120, s5, v120
	v_add_lshl_u32 v120, v120, s14, 1
	s_mov_b64 exec, s[4:5]
	global_store_short v120, v167, s[12:13]
	s_mov_b64 exec, -1
	s_add_u32 s14, s14, s6
	v_cmp_gt_u32_e64 s[4:5], s33, v13
	v_cmp_eq_u32_e32 vcc, s33, v13
	s_cbranch_vccz .Ltk_c13
	s_bcnt1_i32_b64 s7, vcc
	v_mbcnt_lo_u32_b32 v121, vcc_lo, 0
	v_mbcnt_hi_u32_b32 v121, vcc_hi, v121
	v_cmp_gt_u32_e64 s[2:3], s82, v121
	s_sub_i32 s82, s82, s7
	s_max_i32 s82, s82, 0
	s_and_b64 s[2:3], s[2:3], vcc
	s_or_b64 s[4:5], s[4:5], s[2:3]
.Ltk_c13:
	s_bcnt1_i32_b64 s6, s[4:5]
	v_mbcnt_lo_u32_b32 v120, s4, 0
	v_mbcnt_hi_u32_b32 v120, s5, v120
	v_add_lshl_u32 v120, v120, s14, 1
	s_mov_b64 exec, s[4:5]
	global_store_short v120, v168, s[12:13]
	s_mov_b64 exec, -1
	s_add_u32 s14, s14, s6
	v_cmp_gt_u32_e64 s[4:5], s33, v14
	v_cmp_eq_u32_e32 vcc, s33, v14
	s_cbranch_vccz .Ltk_c14
	s_bcnt1_i32_b64 s7, vcc
	v_mbcnt_lo_u32_b32 v121, vcc_lo, 0
	v_mbcnt_hi_u32_b32 v121, vcc_hi, v121
	v_cmp_gt_u32_e64 s[2:3], s82, v121
	s_sub_i32 s82, s82, s7
	s_max_i32 s82, s82, 0
	s_and_b64 s[2:3], s[2:3], vcc
	s_or_b64 s[4:5], s[4:5], s[2:3]
.Ltk_c14:
	s_bcnt1_i32_b64 s6, s[4:5]
	v_mbcnt_lo_u32_b32 v120, s4, 0
	v_mbcnt_hi_u32_b32 v120, s5, v120
	v_add_lshl_u32 v120, v120, s14, 1
	s_mov_b64 exec, s[4:5]
	global_store_short v120, v169, s[12:13]
	s_mov_b64 exec, -1
	s_add_u32 s14, s14, s6
	v_cmp_gt_u32_e64 s[4:5], s33, v15
	v_cmp_eq_u32_e32 vcc, s33, v15
	s_cbranch_vccz .Ltk_c15
	s_bcnt1_i32_b64 s7, vcc
	v_mbcnt_lo_u32_b32 v121, vcc_lo, 0
	v_mbcnt_hi_u32_b32 v121, vcc_hi, v121
	v_cmp_gt_u32_e64 s[2:3], s82, v121
	s_sub_i32 s82, s82, s7
	s_max_i32 s82, s82, 0
	s_and_b64 s[2:3], s[2:3], vcc
	s_or_b64 s[4:5], s[4:5], s[2:3]
.Ltk_c15:
	s_bcnt1_i32_b64 s6, s[4:5]
	v_mbcnt_lo_u32_b32 v120, s4, 0
	v_mbcnt_hi_u32_b32 v120, s5, v120
	v_add_lshl_u32 v120, v120, s14, 1
	s_mov_b64 exec, s[4:5]
	global_store_short v120, v170, s[12:13]
	s_mov_b64 exec, -1
	s_add_u32 s14, s14, s6
	s_cmp_le_u32 s9, 16
	s_cbranch_scc1 .Ltk_done
	v_cmp_gt_u32_e64 s[4:5], s33, v16
	v_cmp_eq_u32_e32 vcc, s33, v16
	s_cbranch_vccz .Ltk_c16
	s_bcnt1_i32_b64 s7, vcc
	v_mbcnt_lo_u32_b32 v121, vcc_lo, 0
	v_mbcnt_hi_u32_b32 v121, vcc_hi, v121
	v_cmp_gt_u32_e64 s[2:3], s82, v121
	s_sub_i32 s82, s82, s7
	s_max_i32 s82, s82, 0
	s_and_b64 s[2:3], s[2:3], vcc
	s_or_b64 s[4:5], s[4:5], s[2:3]
.Ltk_c16:
	s_bcnt1_i32_b64 s6, s[4:5]
	v_mbcnt_lo_u32_b32 v120, s4, 0
	v_mbcnt_hi_u32_b32 v120, s5, v120
	v_add_lshl_u32 v120, v120, s14, 1
	s_mov_b64 exec, s[4:5]
	global_store_short v120, v171, s[12:13]
	s_mov_b64 exec, -1
	s_add_u32 s14, s14, s6
	v_cmp_gt_u32_e64 s[4:5], s33, v17
	v_cmp_eq_u32_e32 vcc, s33, v17
	s_cbranch_vccz .Ltk_c17
	s_bcnt1_i32_b64 s7, vcc
	v_mbcnt_lo_u32_b32 v121, vcc_lo, 0
	v_mbcnt_hi_u32_b32 v121, vcc_hi, v121
	v_cmp_gt_u32_e64 s[2:3], s82, v121
	s_sub_i32 s82, s82, s7
	s_max_i32 s82, s82, 0
	s_and_b64 s[2:3], s[2:3], vcc
	s_or_b64 s[4:5], s[4:5], s[2:3]
.Ltk_c17:
	s_bcnt1_i32_b64 s6, s[4:5]
	v_mbcnt_lo_u32_b32 v120, s4, 0
	v_mbcnt_hi_u32_b32 v120, s5, v120
	v_add_lshl_u32 v120, v120, s14, 1
	s_mov_b64 exec, s[4:5]
	global_store_short v120, v172, s[12:13]
	s_mov_b64 exec, -1
	s_add_u32 s14, s14, s6
	v_cmp_gt_u32_e64 s[4:5], s33, v18
	v_cmp_eq_u32_e32 vcc, s33, v18
	s_cbranch_vccz .Ltk_c18
	s_bcnt1_i32_b64 s7, vcc
	v_mbcnt_lo_u32_b32 v121, vcc_lo, 0
	v_mbcnt_hi_u32_b32 v121, vcc_hi, v121
	v_cmp_gt_u32_e64 s[2:3], s82, v121
	s_sub_i32 s82, s82, s7
	s_max_i32 s82, s82, 0
	s_and_b64 s[2:3], s[2:3], vcc
	s_or_b64 s[4:5], s[4:5], s[2:3]
.Ltk_c18:
	s_bcnt1_i32_b64 s6, s[4:5]
	v_mbcnt_lo_u32_b32 v120, s4, 0
	v_mbcnt_hi_u32_b32 v120, s5, v120
	v_add_lshl_u32 v120, v120, s14, 1
	s_mov_b64 exec, s[4:5]
	global_store_short v120, v173, s[12:13]
	s_mov_b64 exec, -1
	s_add_u32 s14, s14, s6
	v_cmp_gt_u32_e64 s[4:5], s33, v19
	v_cmp_eq_u32_e32 vcc, s33, v19
	s_cbranch_vccz .Ltk_c19
	s_bcnt1_i32_b64 s7, vcc
	v_mbcnt_lo_u32_b32 v121, vcc_lo, 0
	v_mbcnt_hi_u32_b32 v121, vcc_hi, v121
	v_cmp_gt_u32_e64 s[2:3], s82, v121
	s_sub_i32 s82, s82, s7
	s_max_i32 s82, s82, 0
	s_and_b64 s[2:3], s[2:3], vcc
	s_or_b64 s[4:5], s[4:5], s[2:3]
.Ltk_c19:
	s_bcnt1_i32_b64 s6, s[4:5]
	v_mbcnt_lo_u32_b32 v120, s4, 0
	v_mbcnt_hi_u32_b32 v120, s5, v120
	v_add_lshl_u32 v120, v120, s14, 1
	s_mov_b64 exec, s[4:5]
	global_store_short v120, v174, s[12:13]
	s_mov_b64 exec, -1
	s_add_u32 s14, s14, s6
	s_cmp_le_u32 s9, 20
	s_cbranch_scc1 .Ltk_done
	v_cmp_gt_u32_e64 s[4:5], s33, v20
	v_cmp_eq_u32_e32 vcc, s33, v20
	s_cbranch_vccz .Ltk_c20
	s_bcnt1_i32_b64 s7, vcc
	v_mbcnt_lo_u32_b32 v121, vcc_lo, 0
	v_mbcnt_hi_u32_b32 v121, vcc_hi, v121
	v_cmp_gt_u32_e64 s[2:3], s82, v121
	s_sub_i32 s82, s82, s7
	s_max_i32 s82, s82, 0
	s_and_b64 s[2:3], s[2:3], vcc
	s_or_b64 s[4:5], s[4:5], s[2:3]
; __device__ __forceinline__ void dsa_index_phase(const Params& p, unsigned char* smem) {
;     ...
;                 const unsigned T = prefix;
;                 int running = 0, outpos = 0;
;                 const unsigned long long lt = (lane == 0) ? 0ull : (~0ull >> (64 - lane));
; #pragma unroll
;                 for (int i = 0; i < 32; ++i) {
;                     if (i < ni) {
;                         const unsigned long long eq = __ballot(u[i] == T);
;                         const int rank = running + __popcll(eq & lt);
;                         const bool sel = u[i] > T || (u[i] == T && rank < need);
;                         const unsigned long long sm = __ballot(sel);
;                         running += __popcll(eq);
;                         if (sel) selrow[outpos + __popcll(sm & lt)] = (unsigned short)(i * 64 + lane);
;                         outpos += __popcll(sm);
;                     }
.Ltk_c20:
	s_bcnt1_i32_b64 s6, s[4:5]
	v_mbcnt_lo_u32_b32 v120, s4, 0
	v_mbcnt_hi_u32_b32 v120, s5, v120
	v_add_lshl_u32 v120, v120, s14, 1
	s_mov_b64 exec, s[4:5]
	global_store_short v120, v175, s[12:13]
	s_mov_b64 exec, -1
	s_add_u32 s14, s14, s6
	v_cmp_gt_u32_e64 s[4:5], s33, v21
	v_cmp_eq_u32_e32 vcc, s33, v21
	s_cbranch_vccz .Ltk_c21
	s_bcnt1_i32_b64 s7, vcc
	v_mbcnt_lo_u32_b32 v121, vcc_lo, 0
	v_mbcnt_hi_u32_b32 v121, vcc_hi, v121
	v_cmp_gt_u32_e64 s[2:3], s82, v121
	s_sub_i32 s82, s82, s7
	s_max_i32 s82, s82, 0
	s_and_b64 s[2:3], s[2:3], vcc
	s_or_b64 s[4:5], s[4:5], s[2:3]
.Ltk_c21:
	s_bcnt1_i32_b64 s6, s[4:5]
	v_mbcnt_lo_u32_b32 v120, s4, 0
	v_mbcnt_hi_u32_b32 v120, s5, v120
	v_add_lshl_u32 v120, v120, s14, 1
	s_mov_b64 exec, s[4:5]
	global_store_short v120, v176, s[12:13]
	s_mov_b64 exec, -1
	s_add_u32 s14, s14, s6
	v_cmp_gt_u32_e64 s[4:5], s33, v22
	v_cmp_eq_u32_e32 vcc, s33, v22
	s_cbranch_vccz .Ltk_c22
	s_bcnt1_i32_b64 s7, vcc
	v_mbcnt_lo_u32_b32 v121, vcc_lo, 0
	v_mbcnt_hi_u32_b32 v121, vcc_hi, v121
	v_cmp_gt_u32_e64 s[2:3], s82, v121
	s_sub_i32 s82, s82, s7
	s_max_i32 s82, s82, 0
	s_and_b64 s[2:3], s[2:3], vcc
	s_or_b64 s[4:5], s[4:5], s[2:3]
.Ltk_c22:
	s_bcnt1_i32_b64 s6, s[4:5]
	v_mbcnt_lo_u32_b32 v120, s4, 0
	v_mbcnt_hi_u32_b32 v120, s5, v120
	v_add_lshl_u32 v120, v120, s14, 1
	s_mov_b64 exec, s[4:5]
	global_store_short v120, v177, s[12:13]
	s_mov_b64 exec, -1
	s_add_u32 s14, s14, s6
	v_cmp_gt_u32_e64 s[4:5], s33, v23
	v_cmp_eq_u32_e32 vcc, s33, v23
	s_cbranch_vccz .Ltk_c23
	s_bcnt1_i32_b64 s7, vcc
	v_mbcnt_lo_u32_b32 v121, vcc_lo, 0
	v_mbcnt_hi_u32_b32 v121, vcc_hi, v121
	v_cmp_gt_u32_e64 s[2:3], s82, v121
	s_sub_i32 s82, s82, s7
	s_max_i32 s82, s82, 0
	s_and_b64 s[2:3], s[2:3], vcc
	s_or_b64 s[4:5], s[4:5], s[2:3]
.Ltk_c23:
	s_bcnt1_i32_b64 s6, s[4:5]
	v_mbcnt_lo_u32_b32 v120, s4, 0
	v_mbcnt_hi_u32_b32 v120, s5, v120
	v_add_lshl_u32 v120, v120, s14, 1
	s_mov_b64 exec, s[4:5]
	global_store_short v120, v178, s[12:13]
	s_mov_b64 exec, -1
	s_add_u32 s14, s14, s6
	s_cmp_le_u32 s9, 24
	s_cbranch_scc1 .Ltk_done
	v_cmp_gt_u32_e64 s[4:5], s33, v24
	v_cmp_eq_u32_e32 vcc, s33, v24
	s_cbranch_vccz .Ltk_c24
	s_bcnt1_i32_b64 s7, vcc
	v_mbcnt_lo_u32_b32 v121, vcc_lo, 0
	v_mbcnt_hi_u32_b32 v121, vcc_hi, v121
	v_cmp_gt_u32_e64 s[2:3], s82, v121
	s_sub_i32 s82, s82, s7
	s_max_i32 s82, s82, 0
	s_and_b64 s[2:3], s[2:3], vcc
	s_or_b64 s[4:5], s[4:5], s[2:3]
.Ltk_c24:
	s_bcnt1_i32_b64 s6, s[4:5]
	v_mbcnt_lo_u32_b32 v120, s4, 0
	v_mbcnt_hi_u32_b32 v120, s5, v120
	v_add_lshl_u32 v120, v120, s14, 1
	s_mov_b64 exec, s[4:5]
	global_store_short v120, v179, s[12:13]
	s_mov_b64 exec, -1
	s_add_u32 s14, s14, s6
	v_cmp_gt_u32_e64 s[4:5], s33, v25
	v_cmp_eq_u32_e32 vcc, s33, v25
	s_cbranch_vccz .Ltk_c25
	s_bcnt1_i32_b64 s7, vcc
	v_mbcnt_lo_u32_b32 v121, vcc_lo, 0
	v_mbcnt_hi_u32_b32 v121, vcc_hi, v121
	v_cmp_gt_u32_e64 s[2:3], s82, v121
	s_sub_i32 s82, s82, s7
	s_max_i32 s82, s82, 0
	s_and_b64 s[2:3], s[2:3], vcc
	s_or_b64 s[4:5], s[4:5], s[2:3]
.Ltk_c25:
	s_bcnt1_i32_b64 s6, s[4:5]
	v_mbcnt_lo_u32_b32 v120, s4, 0
	v_mbcnt_hi_u32_b32 v120, s5, v120
	v_add_lshl_u32 v120, v120, s14, 1
	s_mov_b64 exec, s[4:5]
	global_store_short v120, v180, s[12:13]
	s_mov_b64 exec, -1
	s_add_u32 s14, s14, s6
	v_cmp_gt_u32_e64 s[4:5], s33, v26
	v_cmp_eq_u32_e32 vcc, s33, v26
	s_cbranch_vccz .Ltk_c26
	s_bcnt1_i32_b64 s7, vcc
	v_mbcnt_lo_u32_b32 v121, vcc_lo, 0
	v_mbcnt_hi_u32_b32 v121, vcc_hi, v121
	v_cmp_gt_u32_e64 s[2:3], s82, v121
	s_sub_i32 s82, s82, s7
	s_max_i32 s82, s82, 0
	s_and_b64 s[2:3], s[2:3], vcc
	s_or_b64 s[4:5], s[4:5], s[2:3]
; __device__ __forceinline__ void dsa_index_phase(const Params& p, unsigned char* smem) {
;     ...
;             if (t < 256) {
; #pragma unroll
;                 for (int i = 0; i < 4; ++i) { const int pp = i * 64 + lane; selrow[pp] = (unsigned short)(pp <= t ? pp : 0xFFFF); }
;     ...
;                 const unsigned T = prefix;
;                 int running = 0, outpos = 0;
;                 const unsigned long long lt = (lane == 0) ? 0ull : (~0ull >> (64 - lane));
; #pragma unroll
;                 for (int i = 0; i < 32; ++i) {
;                     if (i < ni) {
;                         const unsigned long long eq = __ballot(u[i] == T);
;                         const int rank = running + __popcll(eq & lt);
;                         const bool sel = u[i] > T || (u[i] == T && rank < need);
;                         const unsigned long long sm = __ballot(sel);
;                         running += __popcll(eq);
;                         if (sel) selrow[outpos + __popcll(sm & lt)] = (unsigned short)(i * 64 + lane);
;                         outpos += __popcll(sm);
;                     }
;                 }
.Ltk_c26:
	s_bcnt1_i32_b64 s6, s[4:5]
	v_mbcnt_lo_u32_b32 v120, s4, 0
	v_mbcnt_hi_u32_b32 v120, s5, v120
	v_add_lshl_u32 v120, v120, s14, 1
	s_mov_b64 exec, s[4:5]
	global_store_short v120, v181, s[12:13]
	s_mov_b64 exec, -1
	s_add_u32 s14, s14, s6
	v_cmp_gt_u32_e64 s[4:5], s33, v27
	v_cmp_eq_u32_e32 vcc, s33, v27
	s_cbranch_vccz .Ltk_c27
	s_bcnt1_i32_b64 s7, vcc
	v_mbcnt_lo_u32_b32 v121, vcc_lo, 0
	v_mbcnt_hi_u32_b32 v121, vcc_hi, v121
	v_cmp_gt_u32_e64 s[2:3], s82, v121
	s_sub_i32 s82, s82, s7
	s_max_i32 s82, s82, 0
	s_and_b64 s[2:3], s[2:3], vcc
	s_or_b64 s[4:5], s[4:5], s[2:3]
.Ltk_c27:
	s_bcnt1_i32_b64 s6, s[4:5]
	v_mbcnt_lo_u32_b32 v120, s4, 0
	v_mbcnt_hi_u32_b32 v120, s5, v120
	v_add_lshl_u32 v120, v120, s14, 1
	s_mov_b64 exec, s[4:5]
	global_store_short v120, v182, s[12:13]
	s_mov_b64 exec, -1
	s_add_u32 s14, s14, s6
	s_cmp_le_u32 s9, 28
	s_cbranch_scc1 .Ltk_done
	v_cmp_gt_u32_e64 s[4:5], s33, v28
	v_cmp_eq_u32_e32 vcc, s33, v28
	s_cbranch_vccz .Ltk_c28
	s_bcnt1_i32_b64 s7, vcc
	v_mbcnt_lo_u32_b32 v121, vcc_lo, 0
	v_mbcnt_hi_u32_b32 v121, vcc_hi, v121
	v_cmp_gt_u32_e64 s[2:3], s82, v121
	s_sub_i32 s82, s82, s7
	s_max_i32 s82, s82, 0
	s_and_b64 s[2:3], s[2:3], vcc
	s_or_b64 s[4:5], s[4:5], s[2:3]
.Ltk_c28:
	s_bcnt1_i32_b64 s6, s[4:5]
	v_mbcnt_lo_u32_b32 v120, s4, 0
	v_mbcnt_hi_u32_b32 v120, s5, v120
	v_add_lshl_u32 v120, v120, s14, 1
	s_mov_b64 exec, s[4:5]
	global_store_short v120, v183, s[12:13]
	s_mov_b64 exec, -1
	s_add_u32 s14, s14, s6
	v_cmp_gt_u32_e64 s[4:5], s33, v29
	v_cmp_eq_u32_e32 vcc, s33, v29
	s_cbranch_vccz .Ltk_c29
	s_bcnt1_i32_b64 s7, vcc
	v_mbcnt_lo_u32_b32 v121, vcc_lo, 0
	v_mbcnt_hi_u32_b32 v121, vcc_hi, v121
	v_cmp_gt_u32_e64 s[2:3], s82, v121
	s_sub_i32 s82, s82, s7
	s_max_i32 s82, s82, 0
	s_and_b64 s[2:3], s[2:3], vcc
	s_or_b64 s[4:5], s[4:5], s[2:3]
.Ltk_c29:
	s_bcnt1_i32_b64 s6, s[4:5]
	v_mbcnt_lo_u32_b32 v120, s4, 0
	v_mbcnt_hi_u32_b32 v120, s5, v120
	v_add_lshl_u32 v120, v120, s14, 1
	s_mov_b64 exec, s[4:5]
	global_store_short v120, v184, s[12:13]
	s_mov_b64 exec, -1
	s_add_u32 s14, s14, s6
	v_cmp_gt_u32_e64 s[4:5], s33, v30
	v_cmp_eq_u32_e32 vcc, s33, v30
	s_cbranch_vccz .Ltk_c30
	s_bcnt1_i32_b64 s7, vcc
	v_mbcnt_lo_u32_b32 v121, vcc_lo, 0
	v_mbcnt_hi_u32_b32 v121, vcc_hi, v121
	v_cmp_gt_u32_e64 s[2:3], s82, v121
	s_sub_i32 s82, s82, s7
	s_max_i32 s82, s82, 0
	s_and_b64 s[2:3], s[2:3], vcc
	s_or_b64 s[4:5], s[4:5], s[2:3]
.Ltk_c30:
	s_bcnt1_i32_b64 s6, s[4:5]
	v_mbcnt_lo_u32_b32 v120, s4, 0
	v_mbcnt_hi_u32_b32 v120, s5, v120
	v_add_lshl_u32 v120, v120, s14, 1
	s_mov_b64 exec, s[4:5]
	global_store_short v120, v185, s[12:13]
	s_mov_b64 exec, -1
	s_add_u32 s14, s14, s6
	v_cmp_gt_u32_e64 s[4:5], s33, v31
	v_cmp_eq_u32_e32 vcc, s33, v31
	s_cbranch_vccz .Ltk_c31
	s_bcnt1_i32_b64 s7, vcc
	v_mbcnt_lo_u32_b32 v121, vcc_lo, 0
	v_mbcnt_hi_u32_b32 v121, vcc_hi, v121
	v_cmp_gt_u32_e64 s[2:3], s82, v121
	s_sub_i32 s82, s82, s7
	s_max_i32 s82, s82, 0
	s_and_b64 s[2:3], s[2:3], vcc
	s_or_b64 s[4:5], s[4:5], s[2:3]
.Ltk_c31:
	s_bcnt1_i32_b64 s6, s[4:5]
	v_mbcnt_lo_u32_b32 v120, s4, 0
	v_mbcnt_hi_u32_b32 v120, s5, v120
	v_add_lshl_u32 v120, v120, s14, 1
	s_mov_b64 exec, s[4:5]
	global_store_short v120, v186, s[12:13]
	s_mov_b64 exec, -1
	s_add_u32 s14, s14, s6
	s_branch .Ltk_done
.Ltk_small:
	v_lshlrev_b32_e32 v120, 1, v124
	v_cmp_ge_u32_e64 s[0:1], s8, v124
	v_cmp_ge_u32_e64 s[2:3], s8, v156
	v_cmp_ge_u32_e64 s[4:5], s8, v157
	v_cmp_ge_u32_e64 s[6:7], s8, v158
	v_cndmask_b32_e64 v0, -1, v124, s[0:1]
	v_cndmask_b32_e64 v1, -1, v156, s[2:3]
	v_cndmask_b32_e64 v2, -1, v157, s[4:5]
	v_cndmask_b32_e64 v3, -1, v158, s[6:7]
	global_store_short v120, v0, s[12:13]
	global_store_short v120, v1, s[12:13] offset:128
	global_store_short v120, v2, s[12:13] offset:256
	global_store_short v120, v3, s[12:13] offset:384
.Ltk_done:
	s_mov_b32 s33, 0x40051592
	s_movk_i32 s82, 0x210
	s_mov_b64 s[0:1], exec
	s_branch .LBB0_125
